# removed the now-unneeded grid barrier between the FFN1 out-projection and the shift-at-W GEMV phase
# speedup vs baseline: 1.0442x; 1.0022x over previous
.LBB0_332:
	s_branch .Lskip_b4
	s_waitcnt vmcnt(0)
	s_waitcnt vmcnt(0)
	s_barrier
	s_and_saveexec_b64 s[0:1], s[80:81]
	s_cbranch_execz .LBB0_384
	s_add_i32 s3, 0, 0x20160
	v_mov_b32_e32 v0, s3
	s_waitcnt vmcnt(0) expcnt(0) lgkmcnt(0)
	ds_read_b32 v2, v0
	s_add_i32 s3, 0, 0x20164
	v_mov_b32_e32 v0, s3
	ds_read_b32 v0, v0
	s_waitcnt lgkmcnt(1)
	v_cmp_ne_u32_e32 vcc, 0, v2
	s_cbranch_vccnz .LBB0_348
	s_add_u32 s4, s72, 0x5c0200
	s_addc_u32 s5, s73, 0
	s_add_u32 s6, s72, 0x5c0400
	s_addc_u32 s7, s73, 0
	s_add_u32 s8, s72, 0x5c0500
	s_addc_u32 s9, s73, 0
	s_add_u32 s10, s72, 0x5c0600
	s_addc_u32 s11, s73, 0
	s_add_u32 s14, s72, 0x5c0700
	s_addc_u32 s15, s73, 0
	s_add_u32 s18, s72, 0x5c0800
	s_addc_u32 s19, s73, 0
	s_add_u32 s38, s72, 0x5c0900
	s_addc_u32 s39, s73, 0
	s_add_u32 s40, s72, 0x5c0a00
	s_addc_u32 s41, s73, 0
	s_add_u32 s42, s72, 0x5c0b00
	s_addc_u32 s43, s73, 0
	s_add_u32 s46, s72, 0x5c0c00
	s_addc_u32 s47, s73, 0
	s_add_u32 s50, s72, 0x5c0d00
	s_addc_u32 s51, s73, 0
	s_add_u32 s52, s72, 0x5c0e00
	s_addc_u32 s53, s73, 0
	s_add_u32 s54, s72, 0x5c0f00
	s_addc_u32 s55, s73, 0
	s_add_u32 s60, s72, 0x5c1000
	s_addc_u32 s61, s73, 0
	s_add_u32 s62, s72, 0x5c1100
	s_addc_u32 s63, s73, 0
	s_add_u32 s64, s72, 0x5c1200
	v_readlane_b32 s3, v242, 8
	s_addc_u32 s65, s73, 0
	s_mul_i32 s3, s75, s3
	s_add_u32 s66, s72, 0x5c1300
	s_mul_i32 s3, s3, s74
	s_addc_u32 s67, s73, 0
	s_mov_b32 s12, 1
	v_mov_b32_e32 v16, 0
	s_branch .LBB0_336

.Lskip_b4:
	s_waitcnt lgkmcnt(0)
	v_mov_b32_e32 v0, v188
	s_barrier
	s_nop 0
	v_readfirstlane_b32 s0, v0
	s_ashr_i32 s3, s0, 6
	v_and_b32_e32 v162, 63, v0
	s_add_i32 s12, s3, s27
	s_cmpk_gt_i32 s12, 0xbff
	v_cmp_eq_u32_e64 s[0:1], 0, v162
	s_cbranch_scc1 .LBB0_403
	v_mbcnt_hi_u32_b32 v0, -1, v189
	v_and_b32_e32 v1, 64, v0
	v_add_u32_e32 v1, 64, v1
	v_xor_b32_e32 v2, 1, v0
	v_cmp_lt_i32_e32 vcc, v2, v1
	s_mov_b64 s[4:5], 0x503000
	v_mov_b32_e32 v169, 0x1c200000
	v_cndmask_b32_e32 v2, v0, v2, vcc
	v_lshlrev_b32_e32 v163, 2, v2
	v_xor_b32_e32 v2, 2, v0
	v_cmp_lt_i32_e32 vcc, v2, v1
	v_mov_b32_e32 v170, 0x1c203000
	v_mov_b32_e32 v171, 0x1c206000
	v_cndmask_b32_e32 v2, v0, v2, vcc
	v_lshlrev_b32_e32 v164, 2, v2
	v_xor_b32_e32 v2, 4, v0
	v_cmp_lt_i32_e32 vcc, v2, v1
	v_mov_b32_e32 v172, 0x1c209000
	v_mov_b32_e32 v173, 0x1c20c000
	v_cndmask_b32_e32 v2, v0, v2, vcc
	v_lshlrev_b32_e32 v165, 2, v2
	v_xor_b32_e32 v2, 8, v0
	v_cmp_lt_i32_e32 vcc, v2, v1
	v_mov_b32_e32 v174, 0x1c20f000
	v_mov_b32_e32 v175, 0x1c212000
	v_cndmask_b32_e32 v2, v0, v2, vcc
	v_lshlrev_b32_e32 v166, 2, v2
	v_xor_b32_e32 v2, 16, v0
	v_cmp_lt_i32_e32 vcc, v2, v1
	v_mov_b32_e32 v176, 0x1c215000
	s_nop 0
	v_cndmask_b32_e32 v2, v0, v2, vcc
	v_lshlrev_b32_e32 v167, 2, v2
	v_xor_b32_e32 v2, 32, v0
	v_cmp_lt_i32_e32 vcc, v2, v1
	v_mov_b32_e32 v1, 0
	s_nop 0
	v_cndmask_b32_e32 v0, v0, v2, vcc
	v_lshlrev_b32_e32 v168, 2, v0
	v_lshlrev_b32_e32 v0, 5, v162
	v_lshl_add_u64 v[0:1], s[72:73], 0, v[0:1]
	v_lshl_add_u64 v[112:113], v[0:1], 0, s[4:5]
	s_mov_b64 s[4:5], 0x503800
	v_lshl_add_u64 v[114:115], v[0:1], 0, s[4:5]
	s_mov_b64 s[4:5], 0x50c000
	v_lshl_add_u64 v[116:117], v[0:1], 0, s[4:5]
	s_mov_b64 s[4:5], 0x50c800
	v_lshl_add_u64 v[118:119], v[0:1], 0, s[4:5]
	s_mov_b64 s[4:5], 0x515000
	v_lshl_add_u64 v[120:121], v[0:1], 0, s[4:5]
	s_mov_b64 s[4:5], 0x515800
	v_lshl_add_u64 v[122:123], v[0:1], 0, s[4:5]
	s_mov_b64 s[4:5], 0x51e000
	v_lshl_add_u64 v[124:125], v[0:1], 0, s[4:5]
	s_mov_b64 s[4:5], 0x51e800
	v_lshl_add_u64 v[126:127], v[0:1], 0, s[4:5]
	s_mov_b64 s[4:5], 0x527000
	v_lshl_add_u64 v[128:129], v[0:1], 0, s[4:5]
	s_mov_b64 s[4:5], 0x527800
	v_lshl_add_u64 v[130:131], v[0:1], 0, s[4:5]
	s_mov_b64 s[4:5], 0x530000
	v_lshl_add_u64 v[132:133], v[0:1], 0, s[4:5]
	s_mov_b64 s[4:5], 0x530800
	v_lshl_add_u64 v[134:135], v[0:1], 0, s[4:5]
	s_mov_b64 s[4:5], 0x539000
	v_lshl_add_u64 v[136:137], v[0:1], 0, s[4:5]
	s_mov_b64 s[4:5], 0x539800
	v_lshl_add_u64 v[138:139], v[0:1], 0, s[4:5]
	s_mov_b64 s[4:5], 0x542000
	v_lshl_add_u64 v[140:141], v[0:1], 0, s[4:5]
	s_mov_b64 s[4:5], 0x542800
	v_lshl_add_u64 v[142:143], v[0:1], 0, s[4:5]
	s_ashr_i32 s4, s3, 31
	s_ashr_i32 s5, s27, 31
	s_add_u32 s8, s3, s27
	s_addc_u32 s9, s4, s5
	s_lshl_b64 s[4:5], s[8:9], 2
	s_ashr_i32 s27, s26, 31
	s_lshl_b64 s[8:9], s[8:9], 11
	s_lshl_b64 s[6:7], s[26:27], 2
	v_lshl_or_b32 v144, v162, 4, s8
	v_mov_b32_e32 v145, s9
	s_lshl_b64 s[8:9], s[26:27], 11
	s_branch .LBB0_387

.LBB0_562:
	ds_read_b128 v[40:43], v187
	ds_read_b128 v[44:47], v187 offset:1024
	ds_read_b128 v[56:59], v187 offset:2048
	ds_read_b128 v[60:63], v187 offset:3072
	ds_read_b128 v[168:171], v190
	ds_read_b128 v[172:175], v190 offset:1024
	ds_read_b128 v[192:195], v190 offset:2048
	ds_read_b128 v[196:199], v190 offset:3072
	s_add_u32 s28, s8, 0xfffc0080
	s_addc_u32 s29, s9, -1
	s_cmp_eq_u32 s66, 12
	s_cselect_b32 s63, s7, s29
	s_cselect_b32 s62, s10, s28
	s_cselect_b32 s61, s47, s65
	s_cselect_b32 s60, s51, s64
	v_lshl_add_u64 v[232:233], s[8:9], 0, v[160:161]
	s_add_i32 m0, s82, 0xc000
	ds_read_b128 v[200:203], v191
	ds_read_b128 v[204:207], v191 offset:1024
	ds_read_b128 v[208:211], v191 offset:2048
	ds_read_b128 v[212:215], v191 offset:3072
	ds_read_b128 v[216:219], v191 offset:4096
	ds_read_b128 v[220:223], v191 offset:5120
	ds_read_b128 v[224:227], v191 offset:6144
	ds_read_b128 v[228:231], v191 offset:7168
	global_load_lds_dwordx4 v[232:233], off
	v_lshl_add_u64 v[232:233], s[8:9], 0, v[162:163]
	s_add_i32 m0, s82, 0xe000
	s_nop 0
	global_load_lds_dwordx4 v[232:233], off
	s_waitcnt vmcnt(8)
	s_waitcnt lgkmcnt(0)
	s_barrier
	s_waitcnt lgkmcnt(0)
	v_mfma_f32_16x16x32_bf16 v[140:143], v[40:43], v[200:203], v[140:143]
	v_mfma_f32_16x16x32_bf16 v[136:139], v[56:59], v[200:203], v[136:139]
	v_mfma_f32_16x16x32_bf16 v[124:127], v[40:43], v[208:211], v[124:127]
	v_mfma_f32_16x16x32_bf16 v[120:123], v[56:59], v[208:211], v[120:123]
	v_mfma_f32_16x16x32_bf16 v[108:111], v[40:43], v[216:219], v[108:111]
	v_mfma_f32_16x16x32_bf16 v[104:107], v[56:59], v[216:219], v[104:107]
	v_mfma_f32_16x16x32_bf16 v[92:95], v[40:43], v[224:227], v[92:95]
	v_mfma_f32_16x16x32_bf16 v[88:91], v[56:59], v[224:227], v[88:91]
	v_mfma_f32_16x16x32_bf16 v[140:143], v[44:47], v[204:207], v[140:143]
	v_mfma_f32_16x16x32_bf16 v[136:139], v[60:63], v[204:207], v[136:139]
	v_mfma_f32_16x16x32_bf16 v[124:127], v[44:47], v[212:215], v[124:127]
	v_mfma_f32_16x16x32_bf16 v[120:123], v[60:63], v[212:215], v[120:123]
	v_mfma_f32_16x16x32_bf16 v[108:111], v[44:47], v[220:223], v[108:111]
	v_mfma_f32_16x16x32_bf16 v[104:107], v[60:63], v[220:223], v[104:107]
	v_mfma_f32_16x16x32_bf16 v[92:95], v[44:47], v[228:231], v[92:95]
	v_mfma_f32_16x16x32_bf16 v[88:91], v[60:63], v[228:231], v[88:91]
	v_mfma_f32_16x16x32_bf16 v[132:135], v[168:171], v[200:203], v[132:135]
	v_mfma_f32_16x16x32_bf16 v[128:131], v[192:195], v[200:203], v[128:131]
	v_mfma_f32_16x16x32_bf16 v[116:119], v[168:171], v[208:211], v[116:119]
	v_mfma_f32_16x16x32_bf16 v[112:115], v[192:195], v[208:211], v[112:115]
	v_mfma_f32_16x16x32_bf16 v[100:103], v[168:171], v[216:219], v[100:103]
	v_mfma_f32_16x16x32_bf16 v[96:99], v[192:195], v[216:219], v[96:99]
	v_mfma_f32_16x16x32_bf16 v[84:87], v[168:171], v[224:227], v[84:87]
	v_mfma_f32_16x16x32_bf16 v[80:83], v[192:195], v[224:227], v[80:83]
	v_mfma_f32_16x16x32_bf16 v[132:135], v[172:175], v[204:207], v[132:135]
	v_mfma_f32_16x16x32_bf16 v[128:131], v[196:199], v[204:207], v[128:131]
	v_mfma_f32_16x16x32_bf16 v[116:119], v[172:175], v[212:215], v[116:119]
	v_mfma_f32_16x16x32_bf16 v[112:115], v[196:199], v[212:215], v[112:115]
	v_mfma_f32_16x16x32_bf16 v[100:103], v[172:175], v[220:223], v[100:103]
	v_mfma_f32_16x16x32_bf16 v[96:99], v[196:199], v[220:223], v[96:99]
	v_mfma_f32_16x16x32_bf16 v[84:87], v[172:175], v[228:231], v[84:87]
	v_mfma_f32_16x16x32_bf16 v[80:83], v[196:199], v[228:231], v[80:83]
	s_barrier
	s_add_i32 s28, s13, s41
	v_lshl_add_u64 v[232:233], s[60:61], 0, v[146:147]
	s_mov_b32 m0, s28
	ds_read_b128 v[200:203], v191 offset:16384
	ds_read_b128 v[204:207], v191 offset:17408
	ds_read_b128 v[208:211], v191 offset:18432
	ds_read_b128 v[212:215], v191 offset:19456
	ds_read_b128 v[216:219], v191 offset:20480
	ds_read_b128 v[220:223], v191 offset:21504
	ds_read_b128 v[224:227], v191 offset:22528
	ds_read_b128 v[228:231], v191 offset:23552
	global_load_lds_dwordx4 v[232:233], off
	s_add_i32 m0, s28, 0x2000
	s_add_u32 s28, s60, 0x40000
	v_lshl_add_u64 v[234:235], s[60:61], 0, v[150:151]
	s_addc_u32 s29, s61, 0
	s_add_i32 s33, s34, s41
	global_load_lds_dwordx4 v[234:235], off
	v_lshl_add_u64 v[236:237], s[28:29], 0, v[146:147]
	s_mov_b32 m0, s33
	v_lshl_add_u64 v[238:239], s[62:63], 0, v[148:149]
	global_load_lds_dwordx4 v[236:237], off
	v_lshl_add_u64 v[236:237], s[28:29], 0, v[150:151]
	s_add_i32 m0, s33, 0x2000
	s_nop 0
	global_load_lds_dwordx4 v[236:237], off
	v_lshl_add_u64 v[236:237], s[62:63], 0, v[144:145]
	s_mov_b32 m0, s82
	s_nop 0
	global_load_lds_dwordx4 v[236:237], off
	s_mov_b32 m0, s83
	s_nop 0
	global_load_lds_dwordx4 v[238:239], off
	s_waitcnt vmcnt(8)
	s_waitcnt lgkmcnt(0)
	s_nop 0
	s_barrier
	s_waitcnt lgkmcnt(0)
	v_mfma_f32_16x16x32_bf16 v[76:79], v[40:43], v[200:203], v[76:79]
	v_mfma_f32_16x16x32_bf16 v[72:75], v[56:59], v[200:203], v[72:75]
	v_mfma_f32_16x16x32_bf16 v[52:55], v[40:43], v[208:211], v[52:55]
	v_mfma_f32_16x16x32_bf16 v[48:51], v[56:59], v[208:211], v[48:51]
	v_mfma_f32_16x16x32_bf16 v[28:31], v[40:43], v[216:219], v[28:31]
	v_mfma_f32_16x16x32_bf16 v[24:27], v[56:59], v[216:219], v[24:27]
	v_mfma_f32_16x16x32_bf16 v[12:15], v[40:43], v[224:227], v[12:15]
	v_mfma_f32_16x16x32_bf16 v[8:11], v[56:59], v[224:227], v[8:11]
	v_mfma_f32_16x16x32_bf16 v[76:79], v[44:47], v[204:207], v[76:79]
	v_mfma_f32_16x16x32_bf16 v[72:75], v[60:63], v[204:207], v[72:75]
	v_mfma_f32_16x16x32_bf16 v[52:55], v[44:47], v[212:215], v[52:55]
	v_mfma_f32_16x16x32_bf16 v[48:51], v[60:63], v[212:215], v[48:51]
	v_mfma_f32_16x16x32_bf16 v[28:31], v[44:47], v[220:223], v[28:31]
	v_mfma_f32_16x16x32_bf16 v[24:27], v[60:63], v[220:223], v[24:27]
	v_mfma_f32_16x16x32_bf16 v[12:15], v[44:47], v[228:231], v[12:15]
	v_mfma_f32_16x16x32_bf16 v[8:11], v[60:63], v[228:231], v[8:11]
	v_mfma_f32_16x16x32_bf16 v[36:39], v[168:171], v[208:211], v[36:39]
	v_mfma_f32_16x16x32_bf16 v[32:35], v[192:195], v[208:211], v[32:35]
	v_mfma_f32_16x16x32_bf16 v[20:23], v[168:171], v[216:219], v[20:23]
	v_mfma_f32_16x16x32_bf16 v[16:19], v[192:195], v[216:219], v[16:19]
	v_mfma_f32_16x16x32_bf16 v[4:7], v[168:171], v[224:227], v[4:7]
	v_mfma_f32_16x16x32_bf16 v[0:3], v[192:195], v[224:227], v[0:3]
	v_mfma_f32_16x16x32_bf16 v[40:43], v[168:171], v[200:203], v[68:71]
	v_mfma_f32_16x16x32_bf16 v[44:47], v[192:195], v[200:203], v[64:67]
	v_mfma_f32_16x16x32_bf16 v[36:39], v[172:175], v[212:215], v[36:39]
	v_mfma_f32_16x16x32_bf16 v[32:35], v[196:199], v[212:215], v[32:35]
	v_mfma_f32_16x16x32_bf16 v[20:23], v[172:175], v[220:223], v[20:23]
	v_mfma_f32_16x16x32_bf16 v[16:19], v[196:199], v[220:223], v[16:19]
	v_mfma_f32_16x16x32_bf16 v[4:7], v[172:175], v[228:231], v[4:7]
	v_mfma_f32_16x16x32_bf16 v[0:3], v[196:199], v[228:231], v[0:3]
	v_mfma_f32_16x16x32_bf16 v[40:43], v[172:175], v[204:207], v[40:43]
	v_mfma_f32_16x16x32_bf16 v[44:47], v[196:199], v[204:207], v[44:47]
	s_barrier
	s_add_i32 s33, 0, 0x18000
	s_add_i32 s56, 0, 0x1c000
	v_add_u32_e32 v68, s33, v176
	v_add_u32_e32 v152, s56, v176
	ds_read_b128 v[56:59], v68
	ds_read_b128 v[60:63], v68 offset:1024
	ds_read_b128 v[64:67], v68 offset:2048
	ds_read_b128 v[68:71], v68 offset:3072
	ds_read_b128 v[168:171], v152
	ds_read_b128 v[172:175], v152 offset:1024
	ds_read_b128 v[192:195], v152 offset:2048
	ds_read_b128 v[196:199], v152 offset:3072
	s_add_u32 s28, s62, 0x40000
	s_addc_u32 s29, s63, 0
	s_mov_b32 m0, s92
	v_lshl_add_u64 v[240:241], s[28:29], 0, v[144:145]
	ds_read_b128 v[200:203], v191 offset:32768
	ds_read_b128 v[204:207], v191 offset:33792
	ds_read_b128 v[208:211], v191 offset:34816
	ds_read_b128 v[212:215], v191 offset:35840
	ds_read_b128 v[216:219], v191 offset:36864
	ds_read_b128 v[220:223], v191 offset:37888
	ds_read_b128 v[224:227], v191 offset:38912
	ds_read_b128 v[228:231], v191 offset:39936
	global_load_lds_dwordx4 v[240:241], off
	v_lshl_add_u64 v[240:241], s[28:29], 0, v[148:149]
	s_mov_b32 m0, s93
	s_nop 0
	global_load_lds_dwordx4 v[240:241], off
	s_waitcnt vmcnt(8)
	s_waitcnt lgkmcnt(0)
	s_nop 0
	s_barrier
	s_waitcnt lgkmcnt(0)
	v_mfma_f32_16x16x32_bf16 v[140:143], v[56:59], v[200:203], v[140:143]
	v_mfma_f32_16x16x32_bf16 v[136:139], v[64:67], v[200:203], v[136:139]
	v_mfma_f32_16x16x32_bf16 v[124:127], v[56:59], v[208:211], v[124:127]
	v_mfma_f32_16x16x32_bf16 v[120:123], v[64:67], v[208:211], v[120:123]
	v_mfma_f32_16x16x32_bf16 v[108:111], v[56:59], v[216:219], v[108:111]
	v_mfma_f32_16x16x32_bf16 v[104:107], v[64:67], v[216:219], v[104:107]
	v_mfma_f32_16x16x32_bf16 v[92:95], v[56:59], v[224:227], v[92:95]
	v_mfma_f32_16x16x32_bf16 v[88:91], v[64:67], v[224:227], v[88:91]
	v_mfma_f32_16x16x32_bf16 v[140:143], v[60:63], v[204:207], v[140:143]
	v_mfma_f32_16x16x32_bf16 v[136:139], v[68:71], v[204:207], v[136:139]
	v_mfma_f32_16x16x32_bf16 v[124:127], v[60:63], v[212:215], v[124:127]
	v_mfma_f32_16x16x32_bf16 v[120:123], v[68:71], v[212:215], v[120:123]
	v_mfma_f32_16x16x32_bf16 v[108:111], v[60:63], v[220:223], v[108:111]
	v_mfma_f32_16x16x32_bf16 v[104:107], v[68:71], v[220:223], v[104:107]
	v_mfma_f32_16x16x32_bf16 v[92:95], v[60:63], v[228:231], v[92:95]
	v_mfma_f32_16x16x32_bf16 v[88:91], v[68:71], v[228:231], v[88:91]
	v_mfma_f32_16x16x32_bf16 v[132:135], v[168:171], v[200:203], v[132:135]
	v_mfma_f32_16x16x32_bf16 v[128:131], v[192:195], v[200:203], v[128:131]
	v_mfma_f32_16x16x32_bf16 v[116:119], v[168:171], v[208:211], v[116:119]
	v_mfma_f32_16x16x32_bf16 v[112:115], v[192:195], v[208:211], v[112:115]
	v_mfma_f32_16x16x32_bf16 v[100:103], v[168:171], v[216:219], v[100:103]
	v_mfma_f32_16x16x32_bf16 v[96:99], v[192:195], v[216:219], v[96:99]
	v_mfma_f32_16x16x32_bf16 v[84:87], v[168:171], v[224:227], v[84:87]
	v_mfma_f32_16x16x32_bf16 v[80:83], v[192:195], v[224:227], v[80:83]
	v_mfma_f32_16x16x32_bf16 v[132:135], v[172:175], v[204:207], v[132:135]
	v_mfma_f32_16x16x32_bf16 v[128:131], v[196:199], v[204:207], v[128:131]
	v_mfma_f32_16x16x32_bf16 v[116:119], v[172:175], v[212:215], v[116:119]
	v_mfma_f32_16x16x32_bf16 v[112:115], v[196:199], v[212:215], v[112:115]
	v_mfma_f32_16x16x32_bf16 v[100:103], v[172:175], v[220:223], v[100:103]
	v_mfma_f32_16x16x32_bf16 v[96:99], v[196:199], v[220:223], v[96:99]
	v_mfma_f32_16x16x32_bf16 v[84:87], v[172:175], v[228:231], v[84:87]
	v_mfma_f32_16x16x32_bf16 v[80:83], v[196:199], v[228:231], v[80:83]
	s_barrier
	s_add_i32 s28, s33, s41
	v_lshl_add_u64 v[232:233], v[232:233], 0, s[16:17]
	s_mov_b32 m0, s28
	ds_read_b128 v[200:203], v191 offset:49152
	ds_read_b128 v[204:207], v191 offset:50176
	ds_read_b128 v[208:211], v191 offset:51200
	ds_read_b128 v[212:215], v191 offset:52224
	ds_read_b128 v[216:219], v191 offset:53248
	ds_read_b128 v[220:223], v191 offset:54272
	ds_read_b128 v[224:227], v191 offset:55296
	ds_read_b128 v[228:231], v191 offset:56320
	global_load_lds_dwordx4 v[232:233], off
	s_add_i32 m0, s28, 0x2000
	s_add_u32 s28, s60, 0x40080
	v_lshl_add_u64 v[232:233], v[234:235], 0, s[16:17]
	s_addc_u32 s29, s61, 0
	s_add_i32 s33, s56, s41
	global_load_lds_dwordx4 v[232:233], off
	v_lshl_add_u64 v[232:233], s[28:29], 0, v[146:147]
	s_mov_b32 m0, s33
	s_nop 0
	global_load_lds_dwordx4 v[232:233], off
	v_lshl_add_u64 v[232:233], s[28:29], 0, v[150:151]
	s_add_i32 m0, s33, 0x2000
	s_nop 0
	global_load_lds_dwordx4 v[232:233], off
	v_lshl_add_u64 v[232:233], v[236:237], 0, s[16:17]
	s_mov_b32 m0, s3
	s_nop 0
	global_load_lds_dwordx4 v[232:233], off
	v_lshl_add_u64 v[232:233], v[238:239], 0, s[16:17]
	s_mov_b32 m0, s78
	s_nop 0
	global_load_lds_dwordx4 v[232:233], off
	s_waitcnt vmcnt(8)
	s_waitcnt lgkmcnt(0)
	s_barrier
	s_waitcnt lgkmcnt(0)
	v_mfma_f32_16x16x32_bf16 v[76:79], v[56:59], v[200:203], v[76:79]
	v_mfma_f32_16x16x32_bf16 v[72:75], v[64:67], v[200:203], v[72:75]
	v_mfma_f32_16x16x32_bf16 v[52:55], v[56:59], v[208:211], v[52:55]
	v_mfma_f32_16x16x32_bf16 v[48:51], v[64:67], v[208:211], v[48:51]
	v_mfma_f32_16x16x32_bf16 v[28:31], v[56:59], v[216:219], v[28:31]
	v_mfma_f32_16x16x32_bf16 v[24:27], v[64:67], v[216:219], v[24:27]
	v_mfma_f32_16x16x32_bf16 v[12:15], v[56:59], v[224:227], v[12:15]
	v_mfma_f32_16x16x32_bf16 v[8:11], v[64:67], v[224:227], v[8:11]
	v_mfma_f32_16x16x32_bf16 v[76:79], v[60:63], v[204:207], v[76:79]
	v_mfma_f32_16x16x32_bf16 v[72:75], v[68:71], v[204:207], v[72:75]
	v_mfma_f32_16x16x32_bf16 v[52:55], v[60:63], v[212:215], v[52:55]
	v_mfma_f32_16x16x32_bf16 v[48:51], v[68:71], v[212:215], v[48:51]
	v_mfma_f32_16x16x32_bf16 v[28:31], v[60:63], v[220:223], v[28:31]
	v_mfma_f32_16x16x32_bf16 v[24:27], v[68:71], v[220:223], v[24:27]
	v_mfma_f32_16x16x32_bf16 v[12:15], v[60:63], v[228:231], v[12:15]
	v_mfma_f32_16x16x32_bf16 v[8:11], v[68:71], v[228:231], v[8:11]
	v_mfma_f32_16x16x32_bf16 v[40:43], v[168:171], v[200:203], v[40:43]
	v_mfma_f32_16x16x32_bf16 v[68:71], v[172:175], v[204:207], v[40:43]
	v_mfma_f32_16x16x32_bf16 v[40:43], v[192:195], v[200:203], v[44:47]
	v_mfma_f32_16x16x32_bf16 v[36:39], v[168:171], v[208:211], v[36:39]
	v_mfma_f32_16x16x32_bf16 v[32:35], v[192:195], v[208:211], v[32:35]
	v_mfma_f32_16x16x32_bf16 v[20:23], v[168:171], v[216:219], v[20:23]
	v_mfma_f32_16x16x32_bf16 v[16:19], v[192:195], v[216:219], v[16:19]
	v_mfma_f32_16x16x32_bf16 v[4:7], v[168:171], v[224:227], v[4:7]
	v_mfma_f32_16x16x32_bf16 v[0:3], v[192:195], v[224:227], v[0:3]
	v_mfma_f32_16x16x32_bf16 v[64:67], v[196:199], v[204:207], v[40:43]
	v_mfma_f32_16x16x32_bf16 v[36:39], v[172:175], v[212:215], v[36:39]
	v_mfma_f32_16x16x32_bf16 v[32:35], v[196:199], v[212:215], v[32:35]
	v_mfma_f32_16x16x32_bf16 v[20:23], v[172:175], v[220:223], v[20:23]
	v_mfma_f32_16x16x32_bf16 v[16:19], v[196:199], v[220:223], v[16:19]
	v_mfma_f32_16x16x32_bf16 v[4:7], v[172:175], v[228:231], v[4:7]
	v_mfma_f32_16x16x32_bf16 v[0:3], v[196:199], v[228:231], v[0:3]
	s_barrier
	s_add_i32 s66, s66, 2
	s_add_u32 s8, s8, 0x100
	s_addc_u32 s9, s9, 0
	s_add_u32 s64, s64, 0x100
	s_addc_u32 s65, s65, 0
	s_cmp_gt_u32 s66, 13
	s_cbranch_scc0 .LBB0_562
	s_and_b64 vcc, exec, s[18:19]
	s_cbranch_vccz .LBB0_565
	s_barrier
